# plus: V-transpose GEMM epilogue column-scale loads loaded once and reused
# baseline (speedup 1.0000x reference)
.LBB0_500:
	s_add_u32 s2, s6, 0xfffe0080
	s_addc_u32 s17, s7, -1
	s_add_i32 s26, 0, 0x10000
	v_add_u32_e32 v156, s26, v145
	ds_read_b128 v[140:143], v156
	ds_read_b128 v[148:151], v156 offset:1024
	ds_read_b128 v[152:155], v156 offset:2048
	ds_read_b128 v[156:159], v156 offset:3072
	s_cmp_eq_u32 s44, 4
	s_cselect_b32 s81, s11, s17
	s_cselect_b32 s80, s24, s2
	s_cselect_b32 s79, s75, s46
	s_cselect_b32 s78, s74, s25
	v_lshl_add_u64 v[164:165], s[6:7], 0, v[136:137]
	s_add_i32 m0, s58, 0xc000
	ds_read_b128 v[160:163], v147
	ds_read_b128 v[188:191], v147 offset:1024
	ds_read_b128 v[192:195], v147 offset:2048
	ds_read_b128 v[196:199], v147 offset:3072
	ds_read_b128 v[200:203], v147 offset:4096
	ds_read_b128 v[216:219], v147 offset:5120
	ds_read_b128 v[220:223], v147 offset:6144
	ds_read_b128 v[224:227], v147 offset:7168
	global_load_lds_dwordx4 v[164:165], off
	v_lshl_add_u64 v[164:165], s[6:7], 0, v[138:139]
	s_add_i32 m0, s58, 0xe000
	s_nop 0
	global_load_lds_dwordx4 v[164:165], off
	s_waitcnt lgkmcnt(8)
	s_barrier
	s_waitcnt lgkmcnt(0)
	s_setprio 1
	s_waitcnt lgkmcnt(0)
	v_mfma_f32_16x16x32_bf16 v[126:129], v[140:143], v[160:163], v[126:129]
	v_mfma_f32_16x16x32_bf16 v[122:125], v[152:155], v[160:163], v[122:125]
	v_mfma_f32_16x16x32_bf16 v[110:113], v[140:143], v[192:195], v[110:113]
	v_mfma_f32_16x16x32_bf16 v[106:109], v[152:155], v[192:195], v[106:109]
	v_mfma_f32_16x16x32_bf16 v[94:97], v[140:143], v[200:203], v[94:97]
	v_mfma_f32_16x16x32_bf16 v[90:93], v[152:155], v[200:203], v[90:93]
	v_mfma_f32_16x16x32_bf16 v[78:81], v[140:143], v[220:223], v[78:81]
	v_mfma_f32_16x16x32_bf16 v[74:77], v[152:155], v[220:223], v[74:77]
	v_mfma_f32_16x16x32_bf16 v[126:129], v[148:151], v[188:191], v[126:129]
	v_mfma_f32_16x16x32_bf16 v[122:125], v[156:159], v[188:191], v[122:125]
	v_mfma_f32_16x16x32_bf16 v[110:113], v[148:151], v[196:199], v[110:113]
	v_mfma_f32_16x16x32_bf16 v[106:109], v[156:159], v[196:199], v[106:109]
	v_mfma_f32_16x16x32_bf16 v[94:97], v[148:151], v[216:219], v[94:97]
	v_mfma_f32_16x16x32_bf16 v[90:93], v[156:159], v[216:219], v[90:93]
	v_mfma_f32_16x16x32_bf16 v[78:81], v[148:151], v[224:227], v[78:81]
	v_mfma_f32_16x16x32_bf16 v[74:77], v[156:159], v[224:227], v[74:77]
	s_setprio 0
	s_barrier
	s_add_i32 s2, 0, 0x14000
	v_add_u32_e32 v164, s2, v145
	s_add_i32 s17, s26, s3
	ds_read_b128 v[228:231], v164
	ds_read_b128 v[232:235], v164 offset:1024
	ds_read_b128 v[236:239], v164 offset:2048
	ds_read_b128 v[240:243], v164 offset:3072
	v_lshl_add_u64 v[164:165], s[78:79], 0, v[0:1]
	s_mov_b32 m0, s17
	v_lshl_add_u64 v[204:205], s[78:79], 0, v[130:131]
	global_load_lds_dwordx4 v[164:165], off
	s_add_i32 m0, s17, 0x2000
	s_nop 0
	global_load_lds_dwordx4 v[204:205], off
	s_barrier
	s_waitcnt lgkmcnt(0)
	s_setprio 1
	s_waitcnt lgkmcnt(0)
	v_mfma_f32_16x16x32_bf16 v[118:121], v[228:231], v[160:163], v[118:121]
	v_mfma_f32_16x16x32_bf16 v[114:117], v[236:239], v[160:163], v[114:117]
	v_mfma_f32_16x16x32_bf16 v[102:105], v[228:231], v[192:195], v[102:105]
	v_mfma_f32_16x16x32_bf16 v[98:101], v[236:239], v[192:195], v[98:101]
	v_mfma_f32_16x16x32_bf16 v[86:89], v[228:231], v[200:203], v[86:89]
	v_mfma_f32_16x16x32_bf16 v[82:85], v[236:239], v[200:203], v[82:85]
	v_mfma_f32_16x16x32_bf16 v[70:73], v[228:231], v[220:223], v[70:73]
	v_mfma_f32_16x16x32_bf16 v[66:69], v[236:239], v[220:223], v[66:69]
	v_mfma_f32_16x16x32_bf16 v[118:121], v[232:235], v[188:191], v[118:121]
	v_mfma_f32_16x16x32_bf16 v[114:117], v[240:243], v[188:191], v[114:117]
	v_mfma_f32_16x16x32_bf16 v[102:105], v[232:235], v[196:199], v[102:105]
	v_mfma_f32_16x16x32_bf16 v[98:101], v[240:243], v[196:199], v[98:101]
	v_mfma_f32_16x16x32_bf16 v[86:89], v[232:235], v[216:219], v[86:89]
	v_mfma_f32_16x16x32_bf16 v[82:85], v[240:243], v[216:219], v[82:85]
	v_mfma_f32_16x16x32_bf16 v[70:73], v[232:235], v[224:227], v[70:73]
	v_mfma_f32_16x16x32_bf16 v[66:69], v[240:243], v[224:227], v[66:69]
	s_setprio 0
	s_mov_b32 m0, s58
	v_lshl_add_u64 v[244:245], s[80:81], 0, v[134:135]
	s_barrier
	ds_read_b128 v[160:163], v147 offset:16384
	ds_read_b128 v[188:191], v147 offset:17408
	ds_read_b128 v[192:195], v147 offset:18432
	ds_read_b128 v[196:199], v147 offset:19456
	ds_read_b128 v[200:203], v147 offset:20480
	ds_read_b128 v[216:219], v147 offset:21504
	ds_read_b128 v[220:223], v147 offset:22528
	ds_read_b128 v[224:227], v147 offset:23552
	global_load_lds_dwordx4 v[244:245], off
	v_lshl_add_u64 v[246:247], s[80:81], 0, v[132:133]
	s_mov_b32 m0, s69
	s_nop 0
	global_load_lds_dwordx4 v[246:247], off
	s_barrier
	s_waitcnt lgkmcnt(0)
	s_setprio 1
	s_waitcnt lgkmcnt(0)
	v_mfma_f32_16x16x32_bf16 v[62:65], v[140:143], v[160:163], v[62:65]
	v_mfma_f32_16x16x32_bf16 v[58:61], v[152:155], v[160:163], v[58:61]
	v_mfma_f32_16x16x32_bf16 v[54:57], v[140:143], v[192:195], v[54:57]
	v_mfma_f32_16x16x32_bf16 v[46:49], v[152:155], v[192:195], v[46:49]
	v_mfma_f32_16x16x32_bf16 v[38:41], v[140:143], v[200:203], v[38:41]
	v_mfma_f32_16x16x32_bf16 v[30:33], v[152:155], v[200:203], v[30:33]
	v_mfma_f32_16x16x32_bf16 v[22:25], v[140:143], v[220:223], v[22:25]
	v_mfma_f32_16x16x32_bf16 v[14:17], v[152:155], v[220:223], v[14:17]
	v_mfma_f32_16x16x32_bf16 v[62:65], v[148:151], v[188:191], v[62:65]
	v_mfma_f32_16x16x32_bf16 v[58:61], v[156:159], v[188:191], v[58:61]
	v_mfma_f32_16x16x32_bf16 v[54:57], v[148:151], v[196:199], v[54:57]
	v_mfma_f32_16x16x32_bf16 v[46:49], v[156:159], v[196:199], v[46:49]
	v_mfma_f32_16x16x32_bf16 v[38:41], v[148:151], v[216:219], v[38:41]
	v_mfma_f32_16x16x32_bf16 v[30:33], v[156:159], v[216:219], v[30:33]
	v_mfma_f32_16x16x32_bf16 v[22:25], v[148:151], v[224:227], v[22:25]
	v_mfma_f32_16x16x32_bf16 v[14:17], v[156:159], v[224:227], v[14:17]
	s_setprio 0
	s_barrier
	s_add_u32 s26, s78, 0xd0000
	s_addc_u32 s27, s79, 0
	s_add_i32 s2, s2, s3
	v_lshl_add_u64 v[140:141], s[26:27], 0, v[0:1]
	s_mov_b32 m0, s2
	s_nop 0
	global_load_lds_dwordx4 v[140:141], off
	v_lshl_add_u64 v[140:141], s[26:27], 0, v[130:131]
	s_add_i32 m0, s2, 0x2000
	s_nop 0
	global_load_lds_dwordx4 v[140:141], off
	s_waitcnt vmcnt(6)
	s_barrier
	s_setprio 1
	v_mfma_f32_16x16x32_bf16 v[50:53], v[228:231], v[160:163], v[50:53]
	v_mfma_f32_16x16x32_bf16 v[42:45], v[236:239], v[160:163], v[42:45]
	v_mfma_f32_16x16x32_bf16 v[34:37], v[228:231], v[192:195], v[34:37]
	v_mfma_f32_16x16x32_bf16 v[26:29], v[236:239], v[192:195], v[26:29]
	v_mfma_f32_16x16x32_bf16 v[18:21], v[228:231], v[200:203], v[18:21]
	v_mfma_f32_16x16x32_bf16 v[10:13], v[236:239], v[200:203], v[10:13]
	v_mfma_f32_16x16x32_bf16 v[6:9], v[228:231], v[220:223], v[6:9]
	v_mfma_f32_16x16x32_bf16 v[2:5], v[236:239], v[220:223], v[2:5]
	v_mfma_f32_16x16x32_bf16 v[50:53], v[232:235], v[188:191], v[50:53]
	v_mfma_f32_16x16x32_bf16 v[42:45], v[240:243], v[188:191], v[42:45]
	v_mfma_f32_16x16x32_bf16 v[34:37], v[232:235], v[196:199], v[34:37]
	v_mfma_f32_16x16x32_bf16 v[26:29], v[240:243], v[196:199], v[26:29]
	v_mfma_f32_16x16x32_bf16 v[18:21], v[232:235], v[216:219], v[18:21]
	v_mfma_f32_16x16x32_bf16 v[10:13], v[240:243], v[216:219], v[10:13]
	v_mfma_f32_16x16x32_bf16 v[6:9], v[232:235], v[224:227], v[6:9]
	v_mfma_f32_16x16x32_bf16 v[2:5], v[240:243], v[224:227], v[2:5]
	s_setprio 0
	s_add_i32 s2, 0, 0x18000
	v_add_u32_e32 v156, s2, v145
	s_barrier
	ds_read_b128 v[140:143], v156
	ds_read_b128 v[148:151], v156 offset:1024
	ds_read_b128 v[152:155], v156 offset:2048
	ds_read_b128 v[156:159], v156 offset:3072
	s_add_u32 s26, s80, 0x20000
	s_addc_u32 s27, s81, 0
	s_mov_b32 m0, s70
	v_lshl_add_u64 v[228:229], s[26:27], 0, v[134:135]
	ds_read_b128 v[160:163], v147 offset:32768
	ds_read_b128 v[188:191], v147 offset:33792
	ds_read_b128 v[192:195], v147 offset:34816
	ds_read_b128 v[196:199], v147 offset:35840
	ds_read_b128 v[200:203], v147 offset:36864
	ds_read_b128 v[216:219], v147 offset:37888
	ds_read_b128 v[220:223], v147 offset:38912
	ds_read_b128 v[224:227], v147 offset:39936
	global_load_lds_dwordx4 v[228:229], off
	v_lshl_add_u64 v[228:229], s[26:27], 0, v[132:133]
	s_mov_b32 m0, s71
	s_nop 0
	global_load_lds_dwordx4 v[228:229], off
	s_waitcnt lgkmcnt(8)
	s_barrier
	s_waitcnt lgkmcnt(0)
	s_setprio 1
	s_waitcnt lgkmcnt(0)
	v_mfma_f32_16x16x32_bf16 v[126:129], v[140:143], v[160:163], v[126:129]
	v_mfma_f32_16x16x32_bf16 v[122:125], v[152:155], v[160:163], v[122:125]
	v_mfma_f32_16x16x32_bf16 v[110:113], v[140:143], v[192:195], v[110:113]
	v_mfma_f32_16x16x32_bf16 v[106:109], v[152:155], v[192:195], v[106:109]
	v_mfma_f32_16x16x32_bf16 v[94:97], v[140:143], v[200:203], v[94:97]
	v_mfma_f32_16x16x32_bf16 v[90:93], v[152:155], v[200:203], v[90:93]
	v_mfma_f32_16x16x32_bf16 v[78:81], v[140:143], v[220:223], v[78:81]
	v_mfma_f32_16x16x32_bf16 v[74:77], v[152:155], v[220:223], v[74:77]
	v_mfma_f32_16x16x32_bf16 v[126:129], v[148:151], v[188:191], v[126:129]
	v_mfma_f32_16x16x32_bf16 v[122:125], v[156:159], v[188:191], v[122:125]
	v_mfma_f32_16x16x32_bf16 v[110:113], v[148:151], v[196:199], v[110:113]
	v_mfma_f32_16x16x32_bf16 v[106:109], v[156:159], v[196:199], v[106:109]
	v_mfma_f32_16x16x32_bf16 v[94:97], v[148:151], v[216:219], v[94:97]
	v_mfma_f32_16x16x32_bf16 v[90:93], v[156:159], v[216:219], v[90:93]
	v_mfma_f32_16x16x32_bf16 v[78:81], v[148:151], v[224:227], v[78:81]
	v_mfma_f32_16x16x32_bf16 v[74:77], v[156:159], v[224:227], v[74:77]
	s_setprio 0
	s_barrier
	s_add_i32 s17, 0, 0x1c000
	s_add_i32 s2, s2, s3
	v_add_u32_e32 v206, s17, v145
	v_lshl_add_u64 v[164:165], v[164:165], 0, s[28:29]
	s_mov_b32 m0, s2
	ds_read_b128 v[228:231], v206
	ds_read_b128 v[232:235], v206 offset:1024
	ds_read_b128 v[236:239], v206 offset:2048
	ds_read_b128 v[240:243], v206 offset:3072
	global_load_lds_dwordx4 v[164:165], off
	v_lshl_add_u64 v[164:165], v[204:205], 0, s[28:29]
	s_add_i32 m0, s2, 0x2000
	s_nop 0
	global_load_lds_dwordx4 v[164:165], off
	s_barrier
	s_waitcnt lgkmcnt(0)
	s_setprio 1
	s_waitcnt lgkmcnt(0)
	v_mfma_f32_16x16x32_bf16 v[118:121], v[228:231], v[160:163], v[118:121]
	v_mfma_f32_16x16x32_bf16 v[114:117], v[236:239], v[160:163], v[114:117]
	v_mfma_f32_16x16x32_bf16 v[102:105], v[228:231], v[192:195], v[102:105]
	v_mfma_f32_16x16x32_bf16 v[98:101], v[236:239], v[192:195], v[98:101]
	v_mfma_f32_16x16x32_bf16 v[86:89], v[228:231], v[200:203], v[86:89]
	v_mfma_f32_16x16x32_bf16 v[82:85], v[236:239], v[200:203], v[82:85]
	v_mfma_f32_16x16x32_bf16 v[70:73], v[228:231], v[220:223], v[70:73]
	v_mfma_f32_16x16x32_bf16 v[66:69], v[236:239], v[220:223], v[66:69]
	v_mfma_f32_16x16x32_bf16 v[118:121], v[232:235], v[188:191], v[118:121]
	v_mfma_f32_16x16x32_bf16 v[114:117], v[240:243], v[188:191], v[114:117]
	v_mfma_f32_16x16x32_bf16 v[102:105], v[232:235], v[196:199], v[102:105]
	v_mfma_f32_16x16x32_bf16 v[98:101], v[240:243], v[196:199], v[98:101]
	v_mfma_f32_16x16x32_bf16 v[86:89], v[232:235], v[216:219], v[86:89]
	v_mfma_f32_16x16x32_bf16 v[82:85], v[240:243], v[216:219], v[82:85]
	v_mfma_f32_16x16x32_bf16 v[70:73], v[232:235], v[224:227], v[70:73]
	v_mfma_f32_16x16x32_bf16 v[66:69], v[240:243], v[224:227], v[66:69]
	s_setprio 0
	s_mov_b32 m0, s72
	v_lshl_add_u64 v[164:165], v[244:245], 0, s[28:29]
	s_barrier
	ds_read_b128 v[160:163], v147 offset:49152
	ds_read_b128 v[188:191], v147 offset:50176
	ds_read_b128 v[192:195], v147 offset:51200
	ds_read_b128 v[196:199], v147 offset:52224
	ds_read_b128 v[200:203], v147 offset:53248
	ds_read_b128 v[216:219], v147 offset:54272
	ds_read_b128 v[220:223], v147 offset:55296
	ds_read_b128 v[224:227], v147 offset:56320
	global_load_lds_dwordx4 v[164:165], off
	v_lshl_add_u64 v[164:165], v[246:247], 0, s[28:29]
	s_mov_b32 m0, s73
	s_nop 0
	global_load_lds_dwordx4 v[164:165], off
	s_barrier
	s_waitcnt lgkmcnt(0)
	s_setprio 1
	s_waitcnt lgkmcnt(0)
	v_mfma_f32_16x16x32_bf16 v[62:65], v[140:143], v[160:163], v[62:65]
	v_mfma_f32_16x16x32_bf16 v[58:61], v[152:155], v[160:163], v[58:61]
	v_mfma_f32_16x16x32_bf16 v[54:57], v[140:143], v[192:195], v[54:57]
	v_mfma_f32_16x16x32_bf16 v[46:49], v[152:155], v[192:195], v[46:49]
	v_mfma_f32_16x16x32_bf16 v[38:41], v[140:143], v[200:203], v[38:41]
	v_mfma_f32_16x16x32_bf16 v[30:33], v[152:155], v[200:203], v[30:33]
	v_mfma_f32_16x16x32_bf16 v[22:25], v[140:143], v[220:223], v[22:25]
	v_mfma_f32_16x16x32_bf16 v[14:17], v[152:155], v[220:223], v[14:17]
	v_mfma_f32_16x16x32_bf16 v[62:65], v[148:151], v[188:191], v[62:65]
	v_mfma_f32_16x16x32_bf16 v[58:61], v[156:159], v[188:191], v[58:61]
	v_mfma_f32_16x16x32_bf16 v[54:57], v[148:151], v[196:199], v[54:57]
	v_mfma_f32_16x16x32_bf16 v[46:49], v[156:159], v[196:199], v[46:49]
	v_mfma_f32_16x16x32_bf16 v[38:41], v[148:151], v[216:219], v[38:41]
	v_mfma_f32_16x16x32_bf16 v[30:33], v[156:159], v[216:219], v[30:33]
	v_mfma_f32_16x16x32_bf16 v[22:25], v[148:151], v[224:227], v[22:25]
	v_mfma_f32_16x16x32_bf16 v[14:17], v[156:159], v[224:227], v[14:17]
	s_setprio 0
	s_barrier
	s_add_u32 s26, s78, 0xd0080
	s_addc_u32 s27, s79, 0
	s_add_i32 s2, s17, s3
	v_lshl_add_u64 v[140:141], s[26:27], 0, v[0:1]
	s_mov_b32 m0, s2
	s_nop 0
	global_load_lds_dwordx4 v[140:141], off
	v_lshl_add_u64 v[140:141], s[26:27], 0, v[130:131]
	s_add_i32 m0, s2, 0x2000
	s_nop 0
	global_load_lds_dwordx4 v[140:141], off
	s_waitcnt vmcnt(6)
	s_barrier
	s_setprio 1
	v_mfma_f32_16x16x32_bf16 v[50:53], v[228:231], v[160:163], v[50:53]
	v_mfma_f32_16x16x32_bf16 v[42:45], v[236:239], v[160:163], v[42:45]
	v_mfma_f32_16x16x32_bf16 v[34:37], v[228:231], v[192:195], v[34:37]
	v_mfma_f32_16x16x32_bf16 v[26:29], v[236:239], v[192:195], v[26:29]
	v_mfma_f32_16x16x32_bf16 v[18:21], v[228:231], v[200:203], v[18:21]
	v_mfma_f32_16x16x32_bf16 v[10:13], v[236:239], v[200:203], v[10:13]
	v_mfma_f32_16x16x32_bf16 v[6:9], v[228:231], v[220:223], v[6:9]
	v_mfma_f32_16x16x32_bf16 v[2:5], v[236:239], v[220:223], v[2:5]
	v_mfma_f32_16x16x32_bf16 v[50:53], v[232:235], v[188:191], v[50:53]
	v_mfma_f32_16x16x32_bf16 v[42:45], v[240:243], v[188:191], v[42:45]
	v_mfma_f32_16x16x32_bf16 v[34:37], v[232:235], v[196:199], v[34:37]
	v_mfma_f32_16x16x32_bf16 v[26:29], v[240:243], v[196:199], v[26:29]
	v_mfma_f32_16x16x32_bf16 v[18:21], v[232:235], v[216:219], v[18:21]
	v_mfma_f32_16x16x32_bf16 v[10:13], v[240:243], v[216:219], v[10:13]
	v_mfma_f32_16x16x32_bf16 v[6:9], v[232:235], v[224:227], v[6:9]
	v_mfma_f32_16x16x32_bf16 v[2:5], v[240:243], v[224:227], v[2:5]
	s_setprio 0
	s_add_i32 s44, s44, 2
	s_add_u32 s6, s6, 0x100
	s_addc_u32 s7, s7, 0
	s_add_u32 s25, s25, 0x100
	s_addc_u32 s46, s46, 0
	s_cmp_gt_u32 s44, 5
	s_barrier
	s_cbranch_scc0 .LBB0_500
	v_lshl_or_b32 v156, s62, 8, v146
	v_ashrrev_i32_e32 v157, 31, v156
	v_lshl_add_u64 v[140:141], v[156:157], 2, s[38:39]
	global_load_dwordx4 v[200:203], v[140:141], off offset:16
	global_load_dwordx4 v[220:223], v[140:141], off
	global_load_dwordx4 v[228:231], v[140:141], off offset:528
	global_load_dwordx4 v[236:239], v[140:141], off offset:512
	v_lshl_add_u32 v142, s63, 8, v144
	v_ashrrev_i32_e32 v143, 31, v142
	s_mov_b32 s2, 0x400000
	s_mov_b64 s[6:7], 0x400000
	s_mov_b32 s62, s41
	s_mov_b32 s63, s10
	s_mov_b64 s[78:79], s[74:75]
	s_mov_b64 s[80:81], s[76:77]
	s_waitcnt vmcnt(0)
	v_mov_b32_e32 v148, v200
	v_mov_b32_e32 v149, v201
	v_mov_b32_e32 v150, v202
	v_mov_b32_e32 v151, v203
	v_mov_b32_e32 v152, v220
	v_mov_b32_e32 v153, v221
	v_mov_b32_e32 v154, v222
	v_mov_b32_e32 v155, v223
	v_pk_mul_f32 v[122:123], v[122:123], v[148:149]
	v_pk_mul_f32 v[126:127], v[126:127], v[152:153]
	v_pk_mul_f32 v[124:125], v[124:125], v[150:151]
	v_cvt_pk_bf16_f32 v150, v122, v123
	v_lshlrev_b64 v[122:123], 15, v[142:143]
	v_pk_mul_f32 v[128:129], v[128:129], v[154:155]
	v_cvt_pk_bf16_f32 v148, v126, v127
	v_cvt_pk_bf16_f32 v151, v124, v125
	v_lshl_add_u64 v[122:123], s[60:61], 0, v[122:123]
	v_lshlrev_b64 v[126:127], 1, v[156:157]
	v_or_b32_e32 v124, 0x80, v156
	v_cvt_pk_bf16_f32 v149, v128, v129
	v_lshl_add_u64 v[122:123], v[122:123], 0, v[126:127]
	v_ashrrev_i32_e32 v125, 31, v124
	global_store_dwordx4 v[122:123], v[148:151], off
	v_lshl_add_u64 v[124:125], v[124:125], 2, s[38:39]
	s_nop 1
	v_mov_b32_e32 v148, v228
	v_mov_b32_e32 v149, v229
	v_mov_b32_e32 v150, v230
	v_mov_b32_e32 v151, v231
	s_nop 1
	v_mov_b32_e32 v152, v236
	v_mov_b32_e32 v153, v237
	v_mov_b32_e32 v154, v238
	v_mov_b32_e32 v155, v239
	s_nop 0
	v_pk_mul_f32 v[128:129], v[116:117], v[150:151]
	v_pk_mul_f32 v[120:121], v[120:121], v[154:155]
	v_pk_mul_f32 v[118:119], v[118:119], v[152:153]
	v_pk_mul_f32 v[116:117], v[114:115], v[148:149]
	v_cvt_pk_bf16_f32 v114, v118, v119
	v_cvt_pk_bf16_f32 v115, v120, v121
	v_cvt_pk_bf16_f32 v116, v116, v117
	v_cvt_pk_bf16_f32 v117, v128, v129
	global_store_dwordx4 v[122:123], v[114:117], off offset:256
	s_nop 1
	v_mov_b32_e32 v114, v200
	v_mov_b32_e32 v115, v201
	v_mov_b32_e32 v116, v202
	v_mov_b32_e32 v117, v203
	s_nop 0
	s_nop 1
	v_mov_b32_e32 v118, v220
	v_mov_b32_e32 v119, v221
	v_mov_b32_e32 v120, v222
	v_mov_b32_e32 v121, v223
	v_or_b32_e32 v128, 16, v142
	v_ashrrev_i32_e32 v129, 31, v128
	s_nop 0
	v_pk_mul_f32 v[116:117], v[108:109], v[116:117]
	v_pk_mul_f32 v[110:111], v[110:111], v[118:119]
	v_pk_mul_f32 v[108:109], v[106:107], v[114:115]
	v_cvt_pk_bf16_f32 v106, v110, v111
	v_lshlrev_b64 v[110:111], 15, v[128:129]
	v_pk_mul_f32 v[112:113], v[112:113], v[120:121]
	v_lshl_add_u64 v[110:111], s[60:61], 0, v[110:111]
	v_cvt_pk_bf16_f32 v107, v112, v113
	v_cvt_pk_bf16_f32 v108, v108, v109
	v_cvt_pk_bf16_f32 v109, v116, v117
	v_lshl_add_u64 v[114:115], v[110:111], 0, v[126:127]
	global_store_dwordx4 v[114:115], v[106:109], off
	s_nop 1
	v_mov_b32_e32 v106, v228
	v_mov_b32_e32 v107, v229
	v_mov_b32_e32 v108, v230
	v_mov_b32_e32 v109, v231
	s_nop 0
	s_nop 1
	v_mov_b32_e32 v110, v236
	v_mov_b32_e32 v111, v237
	v_mov_b32_e32 v112, v238
	v_mov_b32_e32 v113, v239
	s_nop 0
	v_pk_mul_f32 v[108:109], v[100:101], v[108:109]
	v_pk_mul_f32 v[104:105], v[104:105], v[112:113]
	v_pk_mul_f32 v[102:103], v[102:103], v[110:111]
	v_pk_mul_f32 v[100:101], v[98:99], v[106:107]
	v_cvt_pk_bf16_f32 v98, v102, v103
	v_cvt_pk_bf16_f32 v99, v104, v105
	v_cvt_pk_bf16_f32 v100, v100, v101
	v_cvt_pk_bf16_f32 v101, v108, v109
	global_store_dwordx4 v[114:115], v[98:101], off offset:256
	s_nop 1
	v_mov_b32_e32 v98, v200
	v_mov_b32_e32 v99, v201
	v_mov_b32_e32 v100, v202
	v_mov_b32_e32 v101, v203
	s_nop 0
	s_nop 1
	v_mov_b32_e32 v102, v220
	v_mov_b32_e32 v103, v221
	v_mov_b32_e32 v104, v222
	v_mov_b32_e32 v105, v223
	v_or_b32_e32 v106, 32, v142
	v_ashrrev_i32_e32 v107, 31, v106
	s_nop 0
	v_pk_mul_f32 v[100:101], v[92:93], v[100:101]
	v_pk_mul_f32 v[94:95], v[94:95], v[102:103]
	v_pk_mul_f32 v[92:93], v[90:91], v[98:99]
	v_cvt_pk_bf16_f32 v90, v94, v95
	v_lshlrev_b64 v[94:95], 15, v[106:107]
	v_pk_mul_f32 v[96:97], v[96:97], v[104:105]
	v_lshl_add_u64 v[94:95], s[60:61], 0, v[94:95]
	v_cvt_pk_bf16_f32 v91, v96, v97
	v_cvt_pk_bf16_f32 v92, v92, v93
	v_cvt_pk_bf16_f32 v93, v100, v101
	v_lshl_add_u64 v[98:99], v[94:95], 0, v[126:127]
	global_store_dwordx4 v[98:99], v[90:93], off
	s_nop 1
	v_mov_b32_e32 v90, v228
	v_mov_b32_e32 v91, v229
	v_mov_b32_e32 v92, v230
	v_mov_b32_e32 v93, v231
	s_nop 0
	s_nop 1
	v_mov_b32_e32 v94, v236
	v_mov_b32_e32 v95, v237
	v_mov_b32_e32 v96, v238
	v_mov_b32_e32 v97, v239
	s_nop 0
	v_pk_mul_f32 v[92:93], v[84:85], v[92:93]
	v_pk_mul_f32 v[88:89], v[88:89], v[96:97]
	v_pk_mul_f32 v[86:87], v[86:87], v[94:95]
	v_pk_mul_f32 v[84:85], v[82:83], v[90:91]
	v_cvt_pk_bf16_f32 v82, v86, v87
	v_cvt_pk_bf16_f32 v83, v88, v89
	v_cvt_pk_bf16_f32 v84, v84, v85
	v_cvt_pk_bf16_f32 v85, v92, v93
	global_store_dwordx4 v[98:99], v[82:85], off offset:256
	s_nop 1
	v_mov_b32_e32 v82, v200
	v_mov_b32_e32 v83, v201
	v_mov_b32_e32 v84, v202
	v_mov_b32_e32 v85, v203
	s_nop 0
	s_nop 1
	v_mov_b32_e32 v86, v220
	v_mov_b32_e32 v87, v221
	v_mov_b32_e32 v88, v222
	v_mov_b32_e32 v89, v223
	v_or_b32_e32 v90, 48, v142
	v_ashrrev_i32_e32 v91, 31, v90
	s_nop 0
	v_pk_mul_f32 v[84:85], v[76:77], v[84:85]
	v_pk_mul_f32 v[78:79], v[78:79], v[86:87]
	v_pk_mul_f32 v[76:77], v[74:75], v[82:83]
	v_cvt_pk_bf16_f32 v74, v78, v79
	v_lshlrev_b64 v[78:79], 15, v[90:91]
	v_pk_mul_f32 v[80:81], v[80:81], v[88:89]
	v_lshl_add_u64 v[78:79], s[60:61], 0, v[78:79]
	v_cvt_pk_bf16_f32 v75, v80, v81
	v_cvt_pk_bf16_f32 v76, v76, v77
	v_cvt_pk_bf16_f32 v77, v84, v85
	v_lshl_add_u64 v[82:83], v[78:79], 0, v[126:127]
	global_store_dwordx4 v[82:83], v[74:77], off
	s_nop 1
	v_mov_b32_e32 v74, v228
	v_mov_b32_e32 v75, v229
	v_mov_b32_e32 v76, v230
	v_mov_b32_e32 v77, v231
	s_nop 0
	s_nop 1
	v_mov_b32_e32 v78, v236
	v_mov_b32_e32 v79, v237
	v_mov_b32_e32 v80, v238
	v_mov_b32_e32 v81, v239
	s_nop 0
	v_pk_mul_f32 v[76:77], v[68:69], v[76:77]
	v_pk_mul_f32 v[72:73], v[72:73], v[80:81]
	v_pk_mul_f32 v[70:71], v[70:71], v[78:79]
	v_pk_mul_f32 v[68:69], v[66:67], v[74:75]
	v_cvt_pk_bf16_f32 v66, v70, v71
	v_cvt_pk_bf16_f32 v67, v72, v73
	v_cvt_pk_bf16_f32 v68, v68, v69
	v_cvt_pk_bf16_f32 v69, v76, v77
	global_store_dwordx4 v[82:83], v[66:69], off offset:256
	s_nop 1
	v_mov_b32_e32 v66, v200
	v_mov_b32_e32 v67, v201
	v_mov_b32_e32 v68, v202
	v_mov_b32_e32 v69, v203
	s_nop 0
	s_nop 1
	v_mov_b32_e32 v70, v220
	v_mov_b32_e32 v71, v221
	v_mov_b32_e32 v72, v222
	v_mov_b32_e32 v73, v223
	s_nop 0
	v_pk_mul_f32 v[68:69], v[60:61], v[68:69]
	v_pk_mul_f32 v[62:63], v[62:63], v[70:71]
	v_pk_mul_f32 v[64:65], v[64:65], v[72:73]
	v_pk_mul_f32 v[60:61], v[58:59], v[66:67]
	v_cvt_pk_bf16_f32 v58, v62, v63
	v_add_co_u32_e32 v62, vcc, s2, v122
	v_cvt_pk_bf16_f32 v59, v64, v65
	v_cvt_pk_bf16_f32 v60, v60, v61
	v_cvt_pk_bf16_f32 v61, v68, v69
	v_addc_co_u32_e32 v63, vcc, 0, v123, vcc
	global_store_dwordx4 v[62:63], v[58:61], off
	s_nop 1
	v_mov_b32_e32 v58, v228
	v_mov_b32_e32 v59, v229
	v_mov_b32_e32 v60, v230
	v_mov_b32_e32 v61, v231
	s_nop 0
	s_nop 1
	v_mov_b32_e32 v62, v236
	v_mov_b32_e32 v63, v237
	v_mov_b32_e32 v64, v238
	v_mov_b32_e32 v65, v239
	v_lshl_add_u64 v[66:67], v[122:123], 0, s[6:7]
	s_mov_b32 s2, 0x480000
	s_mov_b64 s[6:7], 0x480000
	s_nop 0
	v_pk_mul_f32 v[60:61], v[44:45], v[60:61]
	v_pk_mul_f32 v[52:53], v[52:53], v[64:65]
	v_pk_mul_f32 v[50:51], v[50:51], v[62:63]
	v_pk_mul_f32 v[44:45], v[42:43], v[58:59]
	v_cvt_pk_bf16_f32 v42, v50, v51
	v_cvt_pk_bf16_f32 v43, v52, v53
	v_cvt_pk_bf16_f32 v44, v44, v45
	v_cvt_pk_bf16_f32 v45, v60, v61
	global_store_dwordx4 v[66:67], v[42:45], off offset:256
	s_nop 1
	v_mov_b32_e32 v42, v200
	v_mov_b32_e32 v43, v201
	v_mov_b32_e32 v44, v202
	v_mov_b32_e32 v45, v203
	s_nop 0
	s_nop 1
	v_mov_b32_e32 v50, v220
	v_mov_b32_e32 v51, v221
	v_mov_b32_e32 v52, v222
	v_mov_b32_e32 v53, v223
	s_nop 0
	v_pk_mul_f32 v[48:49], v[48:49], v[44:45]
	v_pk_mul_f32 v[52:53], v[56:57], v[52:53]
	v_pk_mul_f32 v[50:51], v[54:55], v[50:51]
	v_pk_mul_f32 v[44:45], v[46:47], v[42:43]
	v_add_co_u32_e32 v46, vcc, s2, v122
	v_cvt_pk_bf16_f32 v42, v50, v51
	v_cvt_pk_bf16_f32 v43, v52, v53
	v_cvt_pk_bf16_f32 v44, v44, v45
	v_cvt_pk_bf16_f32 v45, v48, v49
	v_addc_co_u32_e32 v47, vcc, 0, v123, vcc
	global_store_dwordx4 v[46:47], v[42:45], off
	s_nop 1
	v_mov_b32_e32 v42, v228
	v_mov_b32_e32 v43, v229
	v_mov_b32_e32 v44, v230
	v_mov_b32_e32 v45, v231
	s_nop 0
	s_nop 1
	v_mov_b32_e32 v46, v236
	v_mov_b32_e32 v47, v237
	v_mov_b32_e32 v48, v238
	v_mov_b32_e32 v49, v239
	v_lshl_add_u64 v[50:51], v[122:123], 0, s[6:7]
	s_mov_b32 s2, 0x500000
	s_mov_b64 s[6:7], 0x500000
	s_nop 0
	v_pk_mul_f32 v[44:45], v[28:29], v[44:45]
	v_pk_mul_f32 v[36:37], v[36:37], v[48:49]
	v_pk_mul_f32 v[34:35], v[34:35], v[46:47]
	v_pk_mul_f32 v[28:29], v[26:27], v[42:43]
	v_cvt_pk_bf16_f32 v26, v34, v35
	v_cvt_pk_bf16_f32 v27, v36, v37
	v_cvt_pk_bf16_f32 v28, v28, v29
	v_cvt_pk_bf16_f32 v29, v44, v45
	global_store_dwordx4 v[50:51], v[26:29], off offset:256
	s_nop 1
	v_mov_b32_e32 v26, v200
	v_mov_b32_e32 v27, v201
	v_mov_b32_e32 v28, v202
	v_mov_b32_e32 v29, v203
	s_nop 0
	s_nop 1
	v_mov_b32_e32 v34, v220
	v_mov_b32_e32 v35, v221
	v_mov_b32_e32 v36, v222
	v_mov_b32_e32 v37, v223
	s_nop 0
	v_pk_mul_f32 v[32:33], v[32:33], v[28:29]
	v_pk_mul_f32 v[36:37], v[40:41], v[36:37]
	v_pk_mul_f32 v[34:35], v[38:39], v[34:35]
	v_pk_mul_f32 v[28:29], v[30:31], v[26:27]
	v_add_co_u32_e32 v30, vcc, s2, v122
	v_cvt_pk_bf16_f32 v26, v34, v35
	v_cvt_pk_bf16_f32 v27, v36, v37
	v_cvt_pk_bf16_f32 v28, v28, v29
	v_cvt_pk_bf16_f32 v29, v32, v33
	v_addc_co_u32_e32 v31, vcc, 0, v123, vcc
	global_store_dwordx4 v[30:31], v[26:29], off
	s_nop 1
	v_mov_b32_e32 v26, v228
	v_mov_b32_e32 v27, v229
	v_mov_b32_e32 v28, v230
	v_mov_b32_e32 v29, v231
	s_nop 0
	s_nop 1
	v_mov_b32_e32 v30, v236
	v_mov_b32_e32 v31, v237
	v_mov_b32_e32 v32, v238
	v_mov_b32_e32 v33, v239
	v_lshl_add_u64 v[34:35], v[122:123], 0, s[6:7]
	s_mov_b32 s2, 0x580000
	s_mov_b64 s[6:7], 0x580000
	s_nop 0
	v_pk_mul_f32 v[28:29], v[12:13], v[28:29]
	v_pk_mul_f32 v[20:21], v[20:21], v[32:33]
	v_pk_mul_f32 v[18:19], v[18:19], v[30:31]
	v_pk_mul_f32 v[12:13], v[10:11], v[26:27]
	v_cvt_pk_bf16_f32 v10, v18, v19
	v_cvt_pk_bf16_f32 v11, v20, v21
	v_cvt_pk_bf16_f32 v12, v12, v13
	v_cvt_pk_bf16_f32 v13, v28, v29
	global_store_dwordx4 v[34:35], v[10:13], off offset:256
	s_nop 1
	v_mov_b32_e32 v10, v200
	v_mov_b32_e32 v11, v201
	v_mov_b32_e32 v12, v202
	v_mov_b32_e32 v13, v203
	s_nop 0
	s_nop 1
	v_mov_b32_e32 v18, v220
	v_mov_b32_e32 v19, v221
	v_mov_b32_e32 v20, v222
	v_mov_b32_e32 v21, v223
	s_nop 0
	v_pk_mul_f32 v[16:17], v[16:17], v[12:13]
	v_pk_mul_f32 v[20:21], v[24:25], v[20:21]
	v_pk_mul_f32 v[18:19], v[22:23], v[18:19]
	v_pk_mul_f32 v[12:13], v[14:15], v[10:11]
	v_add_co_u32_e32 v14, vcc, s2, v122
	v_cvt_pk_bf16_f32 v10, v18, v19
	v_cvt_pk_bf16_f32 v11, v20, v21
	v_cvt_pk_bf16_f32 v12, v12, v13
	v_cvt_pk_bf16_f32 v13, v16, v17
	v_addc_co_u32_e32 v15, vcc, 0, v123, vcc
	global_store_dwordx4 v[14:15], v[10:13], off
	s_nop 1
	v_mov_b32_e32 v10, v228
	v_mov_b32_e32 v11, v229
	v_mov_b32_e32 v12, v230
	v_mov_b32_e32 v13, v231
	s_nop 0
	s_nop 1
	v_mov_b32_e32 v14, v236
	v_mov_b32_e32 v15, v237
	v_mov_b32_e32 v16, v238
	v_mov_b32_e32 v17, v239
	v_lshl_add_u64 v[18:19], v[122:123], 0, s[6:7]
	s_and_b64 vcc, exec, s[0:1]
	s_nop 0
	v_pk_mul_f32 v[12:13], v[4:5], v[12:13]
	v_pk_mul_f32 v[8:9], v[8:9], v[16:17]
	v_pk_mul_f32 v[6:7], v[6:7], v[14:15]
	v_pk_mul_f32 v[4:5], v[2:3], v[10:11]
	v_cvt_pk_bf16_f32 v2, v6, v7
	v_cvt_pk_bf16_f32 v3, v8, v9
	v_cvt_pk_bf16_f32 v4, v4, v5
	v_cvt_pk_bf16_f32 v5, v12, v13
	global_store_dwordx4 v[18:19], v[2:5], off offset:256
	s_cbranch_vccz .LBB0_491
	v_readlane_b32 s0, v254, 12
	s_waitcnt vmcnt(0)
	v_readlane_b32 s1, v254, 13
	v_readlane_b32 s84, v251, 38
	v_readlane_b32 s18, v253, 0
	s_andn2_b64 vcc, exec, s[0:1]
	v_readlane_b32 s85, v251, 39
	v_readlane_b32 s86, v251, 40
	v_readlane_b32 s87, v251, 41
	v_readlane_b32 s14, v250, 63
	v_readlane_b32 s19, v253, 1
	s_cbranch_vccnz .LBB0_504
	s_barrier
